# selected + sliding-window attention tasks hand written (bulk LDS fragment reads before MFMAs, 3-slot global tile ring with counted waits); gate / previous-output / first-tile loads hoisted to task sta
# speedup vs baseline: 1.0099x; 1.0099x over previous
.LBB0_2063:
	s_or_b64 exec, exec, s[0:1]
	s_cmpk_gt_i32 s90, 0x3ff
	v_readlane_b32 s68, v251, 50
	v_readlane_b32 s69, v251, 51
	s_waitcnt lgkmcnt(0)
	s_barrier
	s_cbranch_scc1 .LBB0_2167
	v_readlane_b32 s0, v251, 7
	v_and_b32_e32 v112, 15, v152
	v_lshrrev_b32_e32 v113, 4, v152
	s_nop 1
	s_and_b32 s34, s0, 3
	s_lshr_b32 s35, s0, 2
	v_lshrrev_b32_e32 v220, 3, v153
	v_and_b32_e32 v221, 7, v153
	v_mul_u32_u24_e32 v114, 0x90, v220
	v_lshl_add_u32 v114, v221, 4, v114
	v_mul_u32_u24_e32 v117, 0x600, v220
	v_lshl_add_u32 v117, v221, 4, v117
	v_lshlrev_b32_e32 v118, 12, v220
	v_lshl_add_u32 v118, v221, 4, v118
	v_mul_u32_u24_e32 v115, 0x90, v112
	v_lshl_add_u32 v116, v113, 3, v115
	v_lshl_add_u32 v115, v113, 4, v115
	v_mov_b32_e32 v226, 0xf149f2ca
	v_mov_b32_e32 v227, 0x7f61b1e6
	v_mov_b32_e32 v238, 0
	s_mov_b32 s26, s90
	s_mov_b32 s27, 0
.Lnsa_task:
	s_lshr_b32 s65, s26, 8
	s_and_b32 s1, s26, 255
	s_and_b32 s28, s1, 31
	s_sub_i32 s2, 31, s28
	s_bitcmp1_b32 s65, 0
	s_cselect_b32 s28, s2, s28
	s_lshr_b32 s29, s1, 5
	s_lshl_b32 s2, s65, 3
	s_add_i32 s29, s29, s2
	s_lshr_b32 s30, s29, 1
	s_and_b32 s31, s29, 1
	s_lshl_b32 s36, s31, 2
	s_add_i32 s36, s36, s34
	s_lshl_b32 s33, s28, 6
	s_mov_b32 s32, s28
	s_lshl_b32 s2, s35, 5
	s_add_i32 s2, s2, s33
	v_add_u32_e32 v86, s2, v112
	v_add_u32_e32 v87, 16, v86
	s_lshl_b32 s3, s30, 11
	v_add_u32_e32 v220, s3, v86
	v_lshlrev_b32_e32 v234, 10, v220
	s_lshl_b32 s4, s36, 7
	v_add_u32_e32 v234, s4, v234
	v_lshl_add_u32 v234, v113, 4, v234
	v_mov_b32_e32 v235, 0
	s_add_u32 s4, s96, 0xe000000
	s_addc_u32 s5, s97, 0
	v_lshl_add_u64 v[234:235], s[4:5], 0, v[234:235]
	global_load_dwordx4 v[160:163], v[234:235], off
	global_load_dwordx4 v[164:167], v[234:235], off offset:64
	v_lshlrev_b32_e32 v236, 8, v86
	v_lshl_add_u32 v236, v113, 6, v236
	s_add_u32 s4, s96, 0x2c00000
	s_addc_u32 s5, s97, 0
	global_load_dwordx4 v[124:127], v236, s[4:5] offset:0
	global_load_dwordx4 v[128:131], v236, s[4:5] offset:16
	global_load_dwordx4 v[132:135], v236, s[4:5] offset:32
	global_load_dwordx4 v[136:139], v236, s[4:5] offset:48
	s_lshl_b32 s6, s29, 11
	v_add_u32_e32 v221, s6, v86
	v_lshlrev_b32_e32 v221, 2, v221
	s_add_u32 s4, s96, 0x2e00000
	s_addc_u32 s5, s97, 0
	global_load_dword v84, v221, s[4:5]
	v_add_u32_e32 v220, s3, v87
	v_lshlrev_b32_e32 v234, 10, v220
	s_lshl_b32 s4, s36, 7
	v_add_u32_e32 v234, s4, v234
	v_lshl_add_u32 v234, v113, 4, v234
	v_mov_b32_e32 v235, 0
	s_add_u32 s4, s96, 0xe000000
	s_addc_u32 s5, s97, 0
	v_lshl_add_u64 v[234:235], s[4:5], 0, v[234:235]
	global_load_dwordx4 v[168:171], v[234:235], off
	global_load_dwordx4 v[172:175], v[234:235], off offset:64
	v_lshlrev_b32_e32 v236, 8, v87
	v_lshl_add_u32 v236, v113, 6, v236
	s_add_u32 s4, s96, 0x2c00000
	s_addc_u32 s5, s97, 0
	global_load_dwordx4 v[140:143], v236, s[4:5] offset:0
	global_load_dwordx4 v[144:147], v236, s[4:5] offset:16
	global_load_dwordx4 v[148:151], v236, s[4:5] offset:32
	global_load_dwordx4 v[154:157], v236, s[4:5] offset:48
	s_lshl_b32 s6, s29, 11
	v_add_u32_e32 v221, s6, v87
	v_lshlrev_b32_e32 v221, 2, v221
	s_add_u32 s4, s96, 0x2e00000
	s_addc_u32 s5, s97, 0
	global_load_dword v85, v221, s[4:5]
	s_lshl_b32 s3, s30, 11
	s_mul_i32 s2, s36, 6
	s_add_i32 s2, s2, 2
	s_add_u32 s8, s96, 0x13000000
	s_addc_u32 s9, s97, 0
	v_add_u32_e32 v223, s3, v86
	v_lshlrev_b32_e32 v223, 6, v223
	v_add_u32_e32 v223, s2, v223
	global_load_ushort v119, v223, s[8:9]
	global_load_ushort v158, v223, s[8:9] offset:2
	v_add_u32_e32 v223, s3, v87
	v_lshlrev_b32_e32 v223, 6, v223
	v_add_u32_e32 v223, s2, v223
	global_load_ushort v159, v223, s[8:9]
	global_load_ushort v233, v223, s[8:9] offset:2
	s_add_u32 s8, s96, 0x9000000
	s_addc_u32 s9, s97, 0
	v_add_u32_e32 v223, s3, v86
	v_lshlrev_b32_e32 v223, 10, v223
	s_lshl_b32 s2, s36, 7
	v_add_u32_e32 v223, s2, v223
	v_lshl_add_u32 v223, v113, 3, v223
	global_load_dwordx2 v[16:17], v223, s[8:9] offset:0
	global_load_dwordx2 v[20:21], v223, s[8:9] offset:32
	global_load_dwordx2 v[24:25], v223, s[8:9] offset:64
	global_load_dwordx2 v[28:29], v223, s[8:9] offset:96
	v_add_u32_e32 v223, s3, v87
	v_lshlrev_b32_e32 v223, 10, v223
	s_lshl_b32 s2, s36, 7
	v_add_u32_e32 v223, s2, v223
	v_lshl_add_u32 v223, v113, 3, v223
	global_load_dwordx2 v[32:33], v223, s[8:9] offset:0
	global_load_dwordx2 v[36:37], v223, s[8:9] offset:32
	global_load_dwordx2 v[40:41], v223, s[8:9] offset:64
	global_load_dwordx2 v[44:45], v223, s[8:9] offset:96
	s_mul_i32 s2, s30, 0x300000
	s_add_u32 s8, s96, 0x10000000
	s_addc_u32 s9, s97, 0
	s_add_u32 s8, s8, s2
	s_addc_u32 s9, s9, 0
	s_lshl_b32 s2, s31, 7
	s_add_u32 s8, s8, s2
	s_addc_u32 s9, s9, 0
	s_add_u32 s10, s8, 0x200
	s_addc_u32 s11, s9, 0
	global_load_dwordx4 v[88:91], v117, s[10:11]
	s_lshl_b32 s2, s29, 18
	s_add_u32 s10, s96, 0x1b200000
	s_addc_u32 s11, s97, 0
	s_add_u32 s10, s10, s2
	s_addc_u32 s11, s11, 0
	global_load_dwordx4 v[92:95], v118, s[10:11]
	s_add_i32 s12, s32, -8
	s_max_i32 s12, s12, 0
	s_mul_i32 s13, s12, 0x18000
	s_add_u32 s10, s8, 0x400
	s_addc_u32 s11, s9, 0
	s_add_u32 s10, s10, s13
	s_addc_u32 s11, s11, 0
	global_load_dwordx4 v[192:195], v117, s[10:11]
	s_lshl_b32 s13, s12, 7
	s_add_u32 s10, s96, 0x1ba00000
	s_addc_u32 s11, s97, 0
	s_add_u32 s10, s10, s2
	s_addc_u32 s11, s11, 0
	s_add_u32 s10, s10, s13
	s_addc_u32 s11, s11, 0
	global_load_dwordx4 v[196:199], v118, s[10:11]
	s_add_i32 s6, s6, s33
	v_add_u32_e32 v221, s6, v152
	v_lshlrev_b32_e32 v221, 2, v221
	global_load_dword v222, v221, s[4:5]
	s_waitcnt vmcnt(0)
	s_nop 1
	v_or_b32_dpp v222, v222, v222 quad_perm:[1,0,3,2] row_mask:0xf bank_mask:0xf bound_ctrl:1
	s_nop 1
	v_or_b32_dpp v222, v222, v222 quad_perm:[2,3,0,1] row_mask:0xf bank_mask:0xf bound_ctrl:1
	s_nop 1
	v_or_b32_dpp v222, v222, v222 row_ror:4 row_mask:0xf bank_mask:0xf bound_ctrl:1
	s_nop 1
	v_or_b32_dpp v222, v222, v222 row_ror:8 row_mask:0xf bank_mask:0xf bound_ctrl:1
	v_mov_b32_e32 v223, v222
	s_nop 1
	v_permlane16_swap_b32_e32 v222, v223
	v_or_b32_e32 v222, v222, v223
	v_mov_b32_e32 v223, v222
	s_nop 1
	v_permlane32_swap_b32_e32 v222, v223
	v_or_b32_e32 v222, v222, v223
	s_nop 0
	v_readfirstlane_b32 s39, v222
	s_mov_b32 s7, 0x3e38aa3b
	v_lshlrev_b32_e32 v220, 16, v160
	v_lshlrev_b32_e32 v221, 16, v164
	v_mul_f32_e32 v222, v221, v125
	v_fma_f32 v222, v220, v124, -v222
	v_mul_f32_e32 v223, v220, v125
	v_fma_f32 v223, v221, v124, v223
	v_mul_f32_e32 v240, s7, v222
	v_mul_f32_e32 v244, s7, v223
	v_and_b32_e32 v220, 0xffff0000, v160
	v_and_b32_e32 v221, 0xffff0000, v164
	v_mul_f32_e32 v222, v221, v127
	v_fma_f32 v222, v220, v126, -v222
	v_mul_f32_e32 v223, v220, v127
	v_fma_f32 v223, v221, v126, v223
	v_mul_f32_e32 v241, s7, v222
	v_mul_f32_e32 v245, s7, v223
	v_lshlrev_b32_e32 v220, 16, v161
	v_lshlrev_b32_e32 v221, 16, v165
	v_mul_f32_e32 v222, v221, v129
	v_fma_f32 v222, v220, v128, -v222
	v_mul_f32_e32 v223, v220, v129
	v_fma_f32 v223, v221, v128, v223
	v_mul_f32_e32 v242, s7, v222
	v_mul_f32_e32 v246, s7, v223
	v_and_b32_e32 v220, 0xffff0000, v161
	v_and_b32_e32 v221, 0xffff0000, v165
	v_mul_f32_e32 v222, v221, v131
	v_fma_f32 v222, v220, v130, -v222
	v_mul_f32_e32 v223, v220, v131
	v_fma_f32 v223, v221, v130, v223
	v_mul_f32_e32 v243, s7, v222
	v_mul_f32_e32 v247, s7, v223
	v_cvt_pk_bf16_f32 v0, v240, v241
	v_cvt_pk_bf16_f32 v1, v242, v243
	v_cvt_pk_bf16_f32 v4, v244, v245
	v_cvt_pk_bf16_f32 v5, v246, v247
	v_lshlrev_b32_e32 v220, 16, v162
	v_lshlrev_b32_e32 v221, 16, v166
	v_mul_f32_e32 v222, v221, v133
	v_fma_f32 v222, v220, v132, -v222
	v_mul_f32_e32 v223, v220, v133
	v_fma_f32 v223, v221, v132, v223
	v_mul_f32_e32 v240, s7, v222
	v_mul_f32_e32 v244, s7, v223
	v_and_b32_e32 v220, 0xffff0000, v162
	v_and_b32_e32 v221, 0xffff0000, v166
	v_mul_f32_e32 v222, v221, v135
	v_fma_f32 v222, v220, v134, -v222
	v_mul_f32_e32 v223, v220, v135
	v_fma_f32 v223, v221, v134, v223
	v_mul_f32_e32 v241, s7, v222
	v_mul_f32_e32 v245, s7, v223
	v_lshlrev_b32_e32 v220, 16, v163
	v_lshlrev_b32_e32 v221, 16, v167
	v_mul_f32_e32 v222, v221, v137
	v_fma_f32 v222, v220, v136, -v222
	v_mul_f32_e32 v223, v220, v137
	v_fma_f32 v223, v221, v136, v223
	v_mul_f32_e32 v242, s7, v222
	v_mul_f32_e32 v246, s7, v223
	v_and_b32_e32 v220, 0xffff0000, v163
	v_and_b32_e32 v221, 0xffff0000, v167
	v_mul_f32_e32 v222, v221, v139
	v_fma_f32 v222, v220, v138, -v222
	v_mul_f32_e32 v223, v220, v139
	v_fma_f32 v223, v221, v138, v223
	v_mul_f32_e32 v243, s7, v222
	v_mul_f32_e32 v247, s7, v223
	v_cvt_pk_bf16_f32 v2, v240, v241
	v_cvt_pk_bf16_f32 v3, v242, v243
	v_cvt_pk_bf16_f32 v6, v244, v245
	v_cvt_pk_bf16_f32 v7, v246, v247
	v_lshlrev_b32_e32 v220, 16, v168
	v_lshlrev_b32_e32 v221, 16, v172
	v_mul_f32_e32 v222, v221, v141
	v_fma_f32 v222, v220, v140, -v222
	v_mul_f32_e32 v223, v220, v141
	v_fma_f32 v223, v221, v140, v223
	v_mul_f32_e32 v240, s7, v222
	v_mul_f32_e32 v244, s7, v223
	v_and_b32_e32 v220, 0xffff0000, v168
	v_and_b32_e32 v221, 0xffff0000, v172
	v_mul_f32_e32 v222, v221, v143
	v_fma_f32 v222, v220, v142, -v222
	v_mul_f32_e32 v223, v220, v143
	v_fma_f32 v223, v221, v142, v223
	v_mul_f32_e32 v241, s7, v222
	v_mul_f32_e32 v245, s7, v223
	v_lshlrev_b32_e32 v220, 16, v169
	v_lshlrev_b32_e32 v221, 16, v173
	v_mul_f32_e32 v222, v221, v145
	v_fma_f32 v222, v220, v144, -v222
	v_mul_f32_e32 v223, v220, v145
	v_fma_f32 v223, v221, v144, v223
	v_mul_f32_e32 v242, s7, v222
	v_mul_f32_e32 v246, s7, v223
	v_and_b32_e32 v220, 0xffff0000, v169
	v_and_b32_e32 v221, 0xffff0000, v173
	v_mul_f32_e32 v222, v221, v147
	v_fma_f32 v222, v220, v146, -v222
	v_mul_f32_e32 v223, v220, v147
	v_fma_f32 v223, v221, v146, v223
	v_mul_f32_e32 v243, s7, v222
	v_mul_f32_e32 v247, s7, v223
	v_cvt_pk_bf16_f32 v8, v240, v241
	v_cvt_pk_bf16_f32 v9, v242, v243
	v_cvt_pk_bf16_f32 v12, v244, v245
	v_cvt_pk_bf16_f32 v13, v246, v247
	v_lshlrev_b32_e32 v220, 16, v170
	v_lshlrev_b32_e32 v221, 16, v174
	v_mul_f32_e32 v222, v221, v149
	v_fma_f32 v222, v220, v148, -v222
	v_mul_f32_e32 v223, v220, v149
	v_fma_f32 v223, v221, v148, v223
	v_mul_f32_e32 v240, s7, v222
	v_mul_f32_e32 v244, s7, v223
	v_and_b32_e32 v220, 0xffff0000, v170
	v_and_b32_e32 v221, 0xffff0000, v174
	v_mul_f32_e32 v222, v221, v151
	v_fma_f32 v222, v220, v150, -v222
	v_mul_f32_e32 v223, v220, v151
	v_fma_f32 v223, v221, v150, v223
	v_mul_f32_e32 v241, s7, v222
	v_mul_f32_e32 v245, s7, v223
	v_lshlrev_b32_e32 v220, 16, v171
	v_lshlrev_b32_e32 v221, 16, v175
	v_mul_f32_e32 v222, v221, v155
	v_fma_f32 v222, v220, v154, -v222
	v_mul_f32_e32 v223, v220, v155
	v_fma_f32 v223, v221, v154, v223
	v_mul_f32_e32 v242, s7, v222
	v_mul_f32_e32 v246, s7, v223
	v_and_b32_e32 v220, 0xffff0000, v171
	v_and_b32_e32 v221, 0xffff0000, v175
	v_mul_f32_e32 v222, v221, v157
	v_fma_f32 v222, v220, v156, -v222
	v_mul_f32_e32 v223, v220, v157
	v_fma_f32 v223, v221, v156, v223
	v_mul_f32_e32 v243, s7, v222
	v_mul_f32_e32 v247, s7, v223
	v_cvt_pk_bf16_f32 v10, v240, v241
	v_cvt_pk_bf16_f32 v11, v242, v243
	v_cvt_pk_bf16_f32 v14, v244, v245
	v_cvt_pk_bf16_f32 v15, v246, v247
	v_and_b32_e32 v19, 0xffff0000, v17
	v_lshlrev_b32_e32 v18, 16, v17
	v_and_b32_e32 v17, 0xffff0000, v16
	v_lshlrev_b32_e32 v16, 16, v16
	v_and_b32_e32 v23, 0xffff0000, v21
	v_lshlrev_b32_e32 v22, 16, v21
	v_and_b32_e32 v21, 0xffff0000, v20
	v_lshlrev_b32_e32 v20, 16, v20
	v_and_b32_e32 v27, 0xffff0000, v25
	v_lshlrev_b32_e32 v26, 16, v25
	v_and_b32_e32 v25, 0xffff0000, v24
	v_lshlrev_b32_e32 v24, 16, v24
	v_and_b32_e32 v31, 0xffff0000, v29
	v_lshlrev_b32_e32 v30, 16, v29
	v_and_b32_e32 v29, 0xffff0000, v28
	v_lshlrev_b32_e32 v28, 16, v28
	v_and_b32_e32 v35, 0xffff0000, v33
	v_lshlrev_b32_e32 v34, 16, v33
	v_and_b32_e32 v33, 0xffff0000, v32
	v_lshlrev_b32_e32 v32, 16, v32
	v_and_b32_e32 v39, 0xffff0000, v37
	v_lshlrev_b32_e32 v38, 16, v37
	v_and_b32_e32 v37, 0xffff0000, v36
	v_lshlrev_b32_e32 v36, 16, v36
	v_and_b32_e32 v43, 0xffff0000, v41
	v_lshlrev_b32_e32 v42, 16, v41
	v_and_b32_e32 v41, 0xffff0000, v40
	v_lshlrev_b32_e32 v40, 16, v40
	v_and_b32_e32 v47, 0xffff0000, v45
	v_lshlrev_b32_e32 v46, 16, v45
	v_and_b32_e32 v45, 0xffff0000, v44
	v_lshlrev_b32_e32 v44, 16, v44
	s_mov_b32 s37, 0
.Lnsa_br:
	s_mul_i32 s2, s30, 0x300000
	s_add_u32 s46, s96, 0x10000000
	s_addc_u32 s47, s97, 0
	s_add_u32 s46, s46, s2
	s_addc_u32 s47, s47, 0
	s_lshl_b32 s2, s31, 7
	s_cmp_eq_u32 s37, 1
	s_mov_b32 s3, 0x200
	s_cselect_b32 s3, 0x400, s3
	s_add_i32 s2, s2, s3
	s_add_u32 s46, s46, s2
	s_addc_u32 s47, s47, 0
	s_cmp_eq_u32 s37, 1
	s_mov_b32 s3, 0x1b200000
	s_cselect_b32 s3, 0x1ba00000, s3
	s_add_u32 s48, s96, s3
	s_addc_u32 s49, s97, 0
	s_lshl_b32 s2, s29, 18
	s_add_u32 s48, s48, s2
	s_addc_u32 s49, s49, 0
	s_lshl_b32 s2, 2, s32
	s_add_i32 s2, s2, -1
	s_cmp_eq_u32 s37, 1
	s_cbranch_scc1 .Lnsa_brw_1
	s_and_b32 s38, s39, s2
	s_branch .Lnsa_brd_2
.Lnsa_brw_1:
	s_mov_b32 s38, s2
	s_cmp_lt_u32 s32, 8
	s_cbranch_scc1 .Lnsa_brd_2
	s_add_i32 s3, s32, -8
	s_lshl_b32 s38, 0x1ff, s3
.Lnsa_brd_2:
	v_mov_b32_e32 v80, v226
	v_mov_b32_e32 v82, 0
	v_mov_b32_e32 v48, 0
	v_mov_b32_e32 v49, 0
	v_mov_b32_e32 v50, 0
	v_mov_b32_e32 v51, 0
	v_mov_b32_e32 v52, 0
	v_mov_b32_e32 v53, 0
	v_mov_b32_e32 v54, 0
	v_mov_b32_e32 v55, 0
	v_mov_b32_e32 v56, 0
	v_mov_b32_e32 v57, 0
	v_mov_b32_e32 v58, 0
	v_mov_b32_e32 v59, 0
	v_mov_b32_e32 v60, 0
	v_mov_b32_e32 v61, 0
	v_mov_b32_e32 v62, 0
	v_mov_b32_e32 v63, 0
	v_mov_b32_e32 v81, v226
	v_mov_b32_e32 v83, 0
	v_mov_b32_e32 v64, 0
	v_mov_b32_e32 v65, 0
	v_mov_b32_e32 v66, 0
	v_mov_b32_e32 v67, 0
	v_mov_b32_e32 v68, 0
	v_mov_b32_e32 v69, 0
	v_mov_b32_e32 v70, 0
	v_mov_b32_e32 v71, 0
	v_mov_b32_e32 v72, 0
	v_mov_b32_e32 v73, 0
	v_mov_b32_e32 v74, 0
	v_mov_b32_e32 v75, 0
	v_mov_b32_e32 v76, 0
	v_mov_b32_e32 v77, 0
	v_mov_b32_e32 v78, 0
	v_mov_b32_e32 v79, 0
	s_ff1_i32_b32 s40, s38
	s_add_i32 s65, s38, -1
	s_and_b32 s38, s38, s65
	s_ff1_i32_b32 s41, s38
	s_add_i32 s65, s38, -1
	s_and_b32 s38, s38, s65
	s_ff1_i32_b32 s42, s38
	s_add_i32 s65, s38, -1
	s_and_b32 s38, s38, s65
	s_cmp_eq_u32 s37, 1
	s_cbranch_scc0 .Lnsa_nopre_3
	v_mov_b32_e32 v88, v192
	v_mov_b32_e32 v92, v196
	v_mov_b32_e32 v89, v193
	v_mov_b32_e32 v93, v197
	v_mov_b32_e32 v90, v194
	v_mov_b32_e32 v94, v198
	v_mov_b32_e32 v91, v195
	v_mov_b32_e32 v95, v199
	s_branch .Lnsa_have0_4
.Lnsa_nopre_3:
	s_cmp_eq_u32 s40, 0
	s_cbranch_scc1 .Lnsa_have0_4
	s_cmp_lt_i32 s40, 0
	s_cbranch_scc1 .Lnsa_noload_5
	s_mul_i32 s65, s40, 0x18000
	s_add_u32 s56, s46, s65
	s_addc_u32 s57, s47, 0
	s_lshl_b32 s65, s40, 7
	s_add_u32 s58, s48, s65
	s_addc_u32 s59, s49, 0
	global_load_dwordx4 v[88:91], v117, s[56:57]
	global_load_dwordx4 v[92:95], v118, s[58:59]
.Lnsa_noload_5:
.Lnsa_have0_4:
	s_cmp_lt_i32 s41, 0
	s_cbranch_scc1 .Lnsa_noload_6
	s_mul_i32 s65, s41, 0x18000
	s_add_u32 s56, s46, s65
	s_addc_u32 s57, s47, 0
	s_lshl_b32 s65, s41, 7
	s_add_u32 s58, s48, s65
	s_addc_u32 s59, s49, 0
	global_load_dwordx4 v[96:99], v117, s[56:57]
	global_load_dwordx4 v[100:103], v118, s[58:59]
.Lnsa_noload_6:
	s_cmp_lt_i32 s42, 0
	s_cbranch_scc1 .Lnsa_noload_7
	s_mul_i32 s65, s42, 0x18000
	s_add_u32 s56, s46, s65
	s_addc_u32 s57, s47, 0
	s_lshl_b32 s65, s42, 7
	s_add_u32 s58, s48, s65
	s_addc_u32 s59, s49, 0
	global_load_dwordx4 v[104:107], v117, s[56:57]
	global_load_dwordx4 v[108:111], v118, s[58:59]
.Lnsa_noload_7:
.Lnsa_loop_8:
	s_cmp_lt_i32 s40, 0
	s_cbranch_scc1 .Lnsa_brk_9
	s_or_b32 s65, s41, s42
	s_cmp_lt_i32 s65, 0
	s_cbranch_scc0 .Lnsa_w4_10
	s_waitcnt vmcnt(0)
	s_branch .Lnsa_wd_11
.Lnsa_w4_10:
	s_waitcnt vmcnt(4)
.Lnsa_wd_11:
	s_and_b32 s65, s27, 1
	s_mul_i32 s50, s65, 0x4800
	s_add_i32 s27, s27, 1
	v_add_u32_e32 v225, s50, v114
	ds_write_b128 v225, v[88:91]
	ds_write_b128 v225, v[92:95] offset:9216
	s_waitcnt lgkmcnt(0)
	s_barrier
	s_mov_b32 s43, s40
	s_ff1_i32_b32 s40, s38
	s_add_i32 s65, s38, -1
	s_and_b32 s38, s38, s65
	s_cmp_lt_i32 s40, 0
	s_cbranch_scc1 .Lnsa_noload_12
	s_mul_i32 s65, s40, 0x18000
	s_add_u32 s56, s46, s65
	s_addc_u32 s57, s47, 0
	s_lshl_b32 s65, s40, 7
	s_add_u32 s58, s48, s65
	s_addc_u32 s59, s49, 0
	global_load_dwordx4 v[88:91], v117, s[56:57]
	global_load_dwordx4 v[92:95], v118, s[58:59]
.Lnsa_noload_12:
	s_lshl_b32 s44, s43, 6
	s_cmp_eq_u32 s37, 1
	s_cbranch_scc1 .Lnsa_selall_13
	s_lshl_b32 s65, 1, s43
	v_and_b32_e32 v220, s65, v84
	v_cmp_ne_u32_e64 s[60:61], 0, v220
	v_and_b32_e32 v220, s65, v85
	v_cmp_ne_u32_e64 s[62:63], 0, v220
	s_branch .Lnsa_seld_14
.Lnsa_selall_13:
	s_mov_b64 s[60:61], exec
	s_mov_b64 s[62:63], exec
.Lnsa_seld_14:
	s_cmp_eq_u32 s43, s32
	s_cbranch_scc1 .Lnsa_part_15
	s_cmp_eq_u32 s37, 1
	s_cbranch_scc0 .Lnsa_inter_16
	s_add_i32 s65, s32, -8
	s_cmp_eq_u32 s43, s65
	s_cbranch_scc1 .Lnsa_part_15
.Lnsa_inter_16:
	v_add_u32_e32 v225, s50, v115
	ds_read_b128 v[160:163], v225 offset:0
	ds_read_b128 v[164:167], v225 offset:64
	ds_read_b128 v[168:171], v225 offset:2304
	ds_read_b128 v[172:175], v225 offset:2368
	ds_read_b128 v[176:179], v225 offset:4608
	ds_read_b128 v[180:183], v225 offset:4672
	ds_read_b128 v[184:187], v225 offset:6912
	ds_read_b128 v[188:191], v225 offset:6976
	s_waitcnt lgkmcnt(0)
	v_mfma_f32_16x16x32_bf16 v[124:127], v[160:163], v[0:3], 0
	v_mfma_f32_16x16x32_bf16 v[128:131], v[168:171], v[0:3], 0
	v_mfma_f32_16x16x32_bf16 v[132:135], v[176:179], v[0:3], 0
	v_mfma_f32_16x16x32_bf16 v[136:139], v[184:187], v[0:3], 0
	v_mfma_f32_16x16x32_bf16 v[124:127], v[164:167], v[4:7], v[124:127]
	v_mfma_f32_16x16x32_bf16 v[128:131], v[172:175], v[4:7], v[128:131]
	v_mfma_f32_16x16x32_bf16 v[132:135], v[180:183], v[4:7], v[132:135]
	v_mfma_f32_16x16x32_bf16 v[136:139], v[188:191], v[4:7], v[136:139]
	v_mfma_f32_16x16x32_bf16 v[140:143], v[160:163], v[8:11], 0
	v_mfma_f32_16x16x32_bf16 v[144:147], v[168:171], v[8:11], 0
	v_mfma_f32_16x16x32_bf16 v[148:151], v[176:179], v[8:11], 0
	v_mfma_f32_16x16x32_bf16 v[154:157], v[184:187], v[8:11], 0
	v_mfma_f32_16x16x32_bf16 v[140:143], v[164:167], v[12:15], v[140:143]
	v_mfma_f32_16x16x32_bf16 v[144:147], v[172:175], v[12:15], v[144:147]
	v_mfma_f32_16x16x32_bf16 v[148:151], v[180:183], v[12:15], v[148:151]
	v_mfma_f32_16x16x32_bf16 v[154:157], v[188:191], v[12:15], v[154:157]
	v_add_u32_e32 v225, s50, v116
	ds_read_b64 v[160:161], v225 offset:9216
	ds_read_b64 v[162:163], v225 offset:9248
	ds_read_b64 v[164:165], v225 offset:9280
	ds_read_b64 v[166:167], v225 offset:9312
	ds_read_b64 v[168:169], v225 offset:11520
	ds_read_b64 v[170:171], v225 offset:11552
	ds_read_b64 v[172:173], v225 offset:11584
	ds_read_b64 v[174:175], v225 offset:11616
	ds_read_b64 v[176:177], v225 offset:13824
	ds_read_b64 v[178:179], v225 offset:13856
	ds_read_b64 v[180:181], v225 offset:13888
	ds_read_b64 v[182:183], v225 offset:13920
	ds_read_b64 v[184:185], v225 offset:16128
	ds_read_b64 v[186:187], v225 offset:16160
	ds_read_b64 v[188:189], v225 offset:16192
	ds_read_b64 v[190:191], v225 offset:16224
	v_max3_f32 v220, v124, v125, v126
	v_max3_f32 v220, v220, v127, v128
	v_max3_f32 v220, v220, v129, v130
	v_max3_f32 v220, v220, v131, v132
	v_max3_f32 v220, v220, v133, v134
	v_max3_f32 v220, v220, v135, v136
	v_max3_f32 v220, v220, v137, v138
	v_max_f32_e32 v220, v220, v139
	v_cndmask_b32_e64 v220, v226, v220, s[60:61]
	v_mov_b32_e32 v221, v220
	s_nop 1
	v_permlane16_swap_b32_e32 v220, v221
	v_max_f32_e32 v220, v220, v221
	v_mov_b32_e32 v221, v220
	s_nop 1
	v_permlane32_swap_b32_e32 v220, v221
	v_max_f32_e32 v220, v220, v221
	v_max_f32_e32 v222, v80, v220
	v_sub_f32_e32 v223, v80, v222
	v_exp_f32_e32 v228, v223
	v_mov_b32_e32 v80, v222
	v_cndmask_b32_e64 v222, v227, v222, s[60:61]
	v_sub_f32_e32 v124, v124, v222
	v_sub_f32_e32 v125, v125, v222
	v_sub_f32_e32 v126, v126, v222
	v_sub_f32_e32 v127, v127, v222
	v_sub_f32_e32 v128, v128, v222
	v_sub_f32_e32 v129, v129, v222
	v_sub_f32_e32 v130, v130, v222
	v_sub_f32_e32 v131, v131, v222
	v_sub_f32_e32 v132, v132, v222
	v_sub_f32_e32 v133, v133, v222
	v_sub_f32_e32 v134, v134, v222
	v_sub_f32_e32 v135, v135, v222
	v_sub_f32_e32 v136, v136, v222
	v_sub_f32_e32 v137, v137, v222
	v_sub_f32_e32 v138, v138, v222
	v_sub_f32_e32 v139, v139, v222
	v_exp_f32_e32 v124, v124
	v_exp_f32_e32 v125, v125
	v_exp_f32_e32 v126, v126
	v_exp_f32_e32 v127, v127
	v_exp_f32_e32 v128, v128
	v_exp_f32_e32 v129, v129
	v_exp_f32_e32 v130, v130
	v_exp_f32_e32 v131, v131
	v_exp_f32_e32 v132, v132
	v_exp_f32_e32 v133, v133
	v_exp_f32_e32 v134, v134
	v_exp_f32_e32 v135, v135
	v_exp_f32_e32 v136, v136
	v_exp_f32_e32 v137, v137
	v_exp_f32_e32 v138, v138
	v_exp_f32_e32 v139, v139
	v_mul_f32_e32 v82, v82, v228
	v_add_f32_e32 v232, 0, v124
	v_add_f32_e32 v232, v232, v125
	v_add_f32_e32 v232, v232, v126
	v_add_f32_e32 v232, v232, v127
	v_add_f32_e32 v232, v232, v128
	v_add_f32_e32 v232, v232, v129
	v_add_f32_e32 v232, v232, v130
	v_add_f32_e32 v232, v232, v131
	v_add_f32_e32 v232, v232, v132
	v_add_f32_e32 v232, v232, v133
	v_add_f32_e32 v232, v232, v134
	v_add_f32_e32 v232, v232, v135
	v_add_f32_e32 v232, v232, v136
	v_add_f32_e32 v232, v232, v137
	v_add_f32_e32 v232, v232, v138
	v_add_f32_e32 v232, v232, v139
	v_add_f32_e32 v82, v82, v232
	v_pk_mul_f32 v[48:49], v[48:49], v[228:229] op_sel_hi:[1,0]
	v_pk_mul_f32 v[50:51], v[50:51], v[228:229] op_sel_hi:[1,0]
	v_pk_mul_f32 v[52:53], v[52:53], v[228:229] op_sel_hi:[1,0]
	v_pk_mul_f32 v[54:55], v[54:55], v[228:229] op_sel_hi:[1,0]
	v_pk_mul_f32 v[56:57], v[56:57], v[228:229] op_sel_hi:[1,0]
	v_pk_mul_f32 v[58:59], v[58:59], v[228:229] op_sel_hi:[1,0]
	v_pk_mul_f32 v[60:61], v[60:61], v[228:229] op_sel_hi:[1,0]
	v_pk_mul_f32 v[62:63], v[62:63], v[228:229] op_sel_hi:[1,0]
	v_cvt_pk_bf16_f32 v204, v124, v125
	v_cvt_pk_bf16_f32 v205, v126, v127
	v_cvt_pk_bf16_f32 v206, v128, v129
	v_cvt_pk_bf16_f32 v207, v130, v131
	v_cvt_pk_bf16_f32 v208, v132, v133
	v_cvt_pk_bf16_f32 v209, v134, v135
	v_cvt_pk_bf16_f32 v210, v136, v137
	v_cvt_pk_bf16_f32 v211, v138, v139
	v_max3_f32 v220, v140, v141, v142
	v_max3_f32 v220, v220, v143, v144
	v_max3_f32 v220, v220, v145, v146
	v_max3_f32 v220, v220, v147, v148
	v_max3_f32 v220, v220, v149, v150
	v_max3_f32 v220, v220, v151, v154
	v_max3_f32 v220, v220, v155, v156
	v_max_f32_e32 v220, v220, v157
	v_cndmask_b32_e64 v220, v226, v220, s[62:63]
	v_mov_b32_e32 v221, v220
	s_nop 1
	v_permlane16_swap_b32_e32 v220, v221
	v_max_f32_e32 v220, v220, v221
	v_mov_b32_e32 v221, v220
	s_nop 1
	v_permlane32_swap_b32_e32 v220, v221
	v_max_f32_e32 v220, v220, v221
	v_max_f32_e32 v222, v81, v220
	v_sub_f32_e32 v223, v81, v222
	v_exp_f32_e32 v230, v223
	v_mov_b32_e32 v81, v222
	v_cndmask_b32_e64 v222, v227, v222, s[62:63]
	v_sub_f32_e32 v140, v140, v222
	v_sub_f32_e32 v141, v141, v222
	v_sub_f32_e32 v142, v142, v222
	v_sub_f32_e32 v143, v143, v222
	v_sub_f32_e32 v144, v144, v222
	v_sub_f32_e32 v145, v145, v222
	v_sub_f32_e32 v146, v146, v222
	v_sub_f32_e32 v147, v147, v222
	v_sub_f32_e32 v148, v148, v222
	v_sub_f32_e32 v149, v149, v222
	v_sub_f32_e32 v150, v150, v222
	v_sub_f32_e32 v151, v151, v222
	v_sub_f32_e32 v154, v154, v222
	v_sub_f32_e32 v155, v155, v222
	v_sub_f32_e32 v156, v156, v222
	v_sub_f32_e32 v157, v157, v222
	v_exp_f32_e32 v140, v140
	v_exp_f32_e32 v141, v141
	v_exp_f32_e32 v142, v142
	v_exp_f32_e32 v143, v143
	v_exp_f32_e32 v144, v144
	v_exp_f32_e32 v145, v145
	v_exp_f32_e32 v146, v146
	v_exp_f32_e32 v147, v147
	v_exp_f32_e32 v148, v148
	v_exp_f32_e32 v149, v149
	v_exp_f32_e32 v150, v150
	v_exp_f32_e32 v151, v151
	v_exp_f32_e32 v154, v154
	v_exp_f32_e32 v155, v155
	v_exp_f32_e32 v156, v156
	v_exp_f32_e32 v157, v157
	v_mul_f32_e32 v83, v83, v230
	v_add_f32_e32 v232, 0, v140
	v_add_f32_e32 v232, v232, v141
	v_add_f32_e32 v232, v232, v142
	v_add_f32_e32 v232, v232, v143
	v_add_f32_e32 v232, v232, v144
	v_add_f32_e32 v232, v232, v145
	v_add_f32_e32 v232, v232, v146
	v_add_f32_e32 v232, v232, v147
	v_add_f32_e32 v232, v232, v148
	v_add_f32_e32 v232, v232, v149
	v_add_f32_e32 v232, v232, v150
	v_add_f32_e32 v232, v232, v151
	v_add_f32_e32 v232, v232, v154
	v_add_f32_e32 v232, v232, v155
	v_add_f32_e32 v232, v232, v156
	v_add_f32_e32 v232, v232, v157
	v_add_f32_e32 v83, v83, v232
	v_pk_mul_f32 v[64:65], v[64:65], v[230:231] op_sel_hi:[1,0]
	v_pk_mul_f32 v[66:67], v[66:67], v[230:231] op_sel_hi:[1,0]
	v_pk_mul_f32 v[68:69], v[68:69], v[230:231] op_sel_hi:[1,0]
	v_pk_mul_f32 v[70:71], v[70:71], v[230:231] op_sel_hi:[1,0]
	v_pk_mul_f32 v[72:73], v[72:73], v[230:231] op_sel_hi:[1,0]
	v_pk_mul_f32 v[74:75], v[74:75], v[230:231] op_sel_hi:[1,0]
	v_pk_mul_f32 v[76:77], v[76:77], v[230:231] op_sel_hi:[1,0]
	v_pk_mul_f32 v[78:79], v[78:79], v[230:231] op_sel_hi:[1,0]
	v_cvt_pk_bf16_f32 v212, v140, v141
	v_cvt_pk_bf16_f32 v213, v142, v143
	v_cvt_pk_bf16_f32 v214, v144, v145
	v_cvt_pk_bf16_f32 v215, v146, v147
	v_cvt_pk_bf16_f32 v216, v148, v149
	v_cvt_pk_bf16_f32 v217, v150, v151
	v_cvt_pk_bf16_f32 v218, v154, v155
	v_cvt_pk_bf16_f32 v219, v156, v157
	s_waitcnt lgkmcnt(0)
	v_mfma_f32_16x16x32_bf16 v[48:51], v[160:163], v[204:207], v[48:51]
	v_mfma_f32_16x16x32_bf16 v[64:67], v[160:163], v[212:215], v[64:67]
	v_mfma_f32_16x16x32_bf16 v[48:51], v[164:167], v[208:211], v[48:51]
	v_mfma_f32_16x16x32_bf16 v[64:67], v[164:167], v[216:219], v[64:67]
	v_mfma_f32_16x16x32_bf16 v[52:55], v[168:171], v[204:207], v[52:55]
	v_mfma_f32_16x16x32_bf16 v[68:71], v[168:171], v[212:215], v[68:71]
	v_mfma_f32_16x16x32_bf16 v[52:55], v[172:175], v[208:211], v[52:55]
	v_mfma_f32_16x16x32_bf16 v[68:71], v[172:175], v[216:219], v[68:71]
	v_mfma_f32_16x16x32_bf16 v[56:59], v[176:179], v[204:207], v[56:59]
	v_mfma_f32_16x16x32_bf16 v[72:75], v[176:179], v[212:215], v[72:75]
	v_mfma_f32_16x16x32_bf16 v[56:59], v[180:183], v[208:211], v[56:59]
	v_mfma_f32_16x16x32_bf16 v[72:75], v[180:183], v[216:219], v[72:75]
	v_mfma_f32_16x16x32_bf16 v[60:63], v[184:187], v[204:207], v[60:63]
	v_mfma_f32_16x16x32_bf16 v[76:79], v[184:187], v[212:215], v[76:79]
	v_mfma_f32_16x16x32_bf16 v[60:63], v[188:191], v[208:211], v[60:63]
	v_mfma_f32_16x16x32_bf16 v[76:79], v[188:191], v[216:219], v[76:79]
	s_branch .Lnsa_fin_17
.Lnsa_part_15:
	v_subrev_u32_e32 v120, s44, v86
	v_lshlrev_b32_e32 v220, 2, v113
	v_sub_u32_e32 v120, v120, v220
	v_add_u32_e32 v122, 0xfffffe00, v120
	v_subrev_u32_e32 v121, s44, v87
	v_lshlrev_b32_e32 v220, 2, v113
	v_sub_u32_e32 v121, v121, v220
	v_add_u32_e32 v123, 0xfffffe00, v121
	s_cmp_eq_u32 s37, 1
	s_cbranch_scc1 .Lnsa_nolo_18
	v_mov_b32_e32 v122, 0xc0000000
	v_mov_b32_e32 v123, 0xc0000000
.Lnsa_nolo_18:
	v_add_u32_e32 v225, s50, v115
	ds_read_b128 v[160:163], v225 offset:0
	ds_read_b128 v[164:167], v225 offset:64
	ds_read_b128 v[168:171], v225 offset:2304
	ds_read_b128 v[172:175], v225 offset:2368
	ds_read_b128 v[176:179], v225 offset:4608
	ds_read_b128 v[180:183], v225 offset:4672
	ds_read_b128 v[184:187], v225 offset:6912
	ds_read_b128 v[188:191], v225 offset:6976
	s_waitcnt lgkmcnt(0)
	v_mfma_f32_16x16x32_bf16 v[124:127], v[160:163], v[0:3], 0
	v_mfma_f32_16x16x32_bf16 v[128:131], v[168:171], v[0:3], 0
	v_mfma_f32_16x16x32_bf16 v[132:135], v[176:179], v[0:3], 0
	v_mfma_f32_16x16x32_bf16 v[136:139], v[184:187], v[0:3], 0
	v_mfma_f32_16x16x32_bf16 v[124:127], v[164:167], v[4:7], v[124:127]
	v_mfma_f32_16x16x32_bf16 v[128:131], v[172:175], v[4:7], v[128:131]
	v_mfma_f32_16x16x32_bf16 v[132:135], v[180:183], v[4:7], v[132:135]
	v_mfma_f32_16x16x32_bf16 v[136:139], v[188:191], v[4:7], v[136:139]
	v_mfma_f32_16x16x32_bf16 v[140:143], v[160:163], v[8:11], 0
	v_mfma_f32_16x16x32_bf16 v[144:147], v[168:171], v[8:11], 0
	v_mfma_f32_16x16x32_bf16 v[148:151], v[176:179], v[8:11], 0
	v_mfma_f32_16x16x32_bf16 v[154:157], v[184:187], v[8:11], 0
	v_mfma_f32_16x16x32_bf16 v[140:143], v[164:167], v[12:15], v[140:143]
	v_mfma_f32_16x16x32_bf16 v[144:147], v[172:175], v[12:15], v[144:147]
	v_mfma_f32_16x16x32_bf16 v[148:151], v[180:183], v[12:15], v[148:151]
	v_mfma_f32_16x16x32_bf16 v[154:157], v[188:191], v[12:15], v[154:157]
	v_add_u32_e32 v225, s50, v116
	ds_read_b64 v[160:161], v225 offset:9216
	ds_read_b64 v[162:163], v225 offset:9248
	ds_read_b64 v[164:165], v225 offset:9280
	ds_read_b64 v[166:167], v225 offset:9312
	ds_read_b64 v[168:169], v225 offset:11520
	ds_read_b64 v[170:171], v225 offset:11552
	ds_read_b64 v[172:173], v225 offset:11584
	ds_read_b64 v[174:175], v225 offset:11616
	ds_read_b64 v[176:177], v225 offset:13824
	ds_read_b64 v[178:179], v225 offset:13856
	ds_read_b64 v[180:181], v225 offset:13888
	ds_read_b64 v[182:183], v225 offset:13920
	ds_read_b64 v[184:185], v225 offset:16128
	ds_read_b64 v[186:187], v225 offset:16160
	ds_read_b64 v[188:189], v225 offset:16192
	ds_read_b64 v[190:191], v225 offset:16224
	v_mov_b32_e32 v224, 0xff800000
	v_mov_b32_e32 v220, v226
	v_cmp_le_i32_e64 s[52:53], 0, v120
	v_cmp_gt_i32_e64 s[54:55], 0, v122
	s_nop 1
	s_and_b64 s[52:53], s[52:53], s[54:55]
	s_and_b64 s[52:53], s[52:53], s[60:61]
	s_nop 1
	v_cndmask_b32_e64 v221, v226, v124, s[52:53]
	v_cndmask_b32_e64 v124, v224, v124, s[52:53]
	v_max_f32_e32 v220, v220, v221
	v_cmp_le_i32_e64 s[52:53], 1, v120
	v_cmp_gt_i32_e64 s[54:55], 1, v122
	s_nop 1
	s_and_b64 s[52:53], s[52:53], s[54:55]
	s_and_b64 s[52:53], s[52:53], s[60:61]
	s_nop 1
	v_cndmask_b32_e64 v221, v226, v125, s[52:53]
	v_cndmask_b32_e64 v125, v224, v125, s[52:53]
	v_max_f32_e32 v220, v220, v221
	v_cmp_le_i32_e64 s[52:53], 2, v120
	v_cmp_gt_i32_e64 s[54:55], 2, v122
	s_nop 1
	s_and_b64 s[52:53], s[52:53], s[54:55]
	s_and_b64 s[52:53], s[52:53], s[60:61]
	s_nop 1
	v_cndmask_b32_e64 v221, v226, v126, s[52:53]
	v_cndmask_b32_e64 v126, v224, v126, s[52:53]
	v_max_f32_e32 v220, v220, v221
	v_cmp_le_i32_e64 s[52:53], 3, v120
	v_cmp_gt_i32_e64 s[54:55], 3, v122
	s_nop 1
	s_and_b64 s[52:53], s[52:53], s[54:55]
	s_and_b64 s[52:53], s[52:53], s[60:61]
	s_nop 1
	v_cndmask_b32_e64 v221, v226, v127, s[52:53]
	v_cndmask_b32_e64 v127, v224, v127, s[52:53]
	v_max_f32_e32 v220, v220, v221
	v_cmp_le_i32_e64 s[52:53], 16, v120
	v_cmp_gt_i32_e64 s[54:55], 16, v122
	s_nop 1
	s_and_b64 s[52:53], s[52:53], s[54:55]
	s_and_b64 s[52:53], s[52:53], s[60:61]
	s_nop 1
	v_cndmask_b32_e64 v221, v226, v128, s[52:53]
	v_cndmask_b32_e64 v128, v224, v128, s[52:53]
	v_max_f32_e32 v220, v220, v221
	v_cmp_le_i32_e64 s[52:53], 17, v120
	v_cmp_gt_i32_e64 s[54:55], 17, v122
	s_nop 1
	s_and_b64 s[52:53], s[52:53], s[54:55]
	s_and_b64 s[52:53], s[52:53], s[60:61]
	s_nop 1
	v_cndmask_b32_e64 v221, v226, v129, s[52:53]
	v_cndmask_b32_e64 v129, v224, v129, s[52:53]
	v_max_f32_e32 v220, v220, v221
	v_cmp_le_i32_e64 s[52:53], 18, v120
	v_cmp_gt_i32_e64 s[54:55], 18, v122
	s_nop 1
	s_and_b64 s[52:53], s[52:53], s[54:55]
	s_and_b64 s[52:53], s[52:53], s[60:61]
	s_nop 1
	v_cndmask_b32_e64 v221, v226, v130, s[52:53]
	v_cndmask_b32_e64 v130, v224, v130, s[52:53]
	v_max_f32_e32 v220, v220, v221
	v_cmp_le_i32_e64 s[52:53], 19, v120
	v_cmp_gt_i32_e64 s[54:55], 19, v122
	s_nop 1
	s_and_b64 s[52:53], s[52:53], s[54:55]
	s_and_b64 s[52:53], s[52:53], s[60:61]
	s_nop 1
	v_cndmask_b32_e64 v221, v226, v131, s[52:53]
	v_cndmask_b32_e64 v131, v224, v131, s[52:53]
	v_max_f32_e32 v220, v220, v221
	v_cmp_le_i32_e64 s[52:53], 32, v120
	v_cmp_gt_i32_e64 s[54:55], 32, v122
	s_nop 1
	s_and_b64 s[52:53], s[52:53], s[54:55]
	s_and_b64 s[52:53], s[52:53], s[60:61]
	s_nop 1
	v_cndmask_b32_e64 v221, v226, v132, s[52:53]
	v_cndmask_b32_e64 v132, v224, v132, s[52:53]
	v_max_f32_e32 v220, v220, v221
	v_cmp_le_i32_e64 s[52:53], 33, v120
	v_cmp_gt_i32_e64 s[54:55], 33, v122
	s_nop 1
	s_and_b64 s[52:53], s[52:53], s[54:55]
	s_and_b64 s[52:53], s[52:53], s[60:61]
	s_nop 1
	v_cndmask_b32_e64 v221, v226, v133, s[52:53]
	v_cndmask_b32_e64 v133, v224, v133, s[52:53]
	v_max_f32_e32 v220, v220, v221
	v_cmp_le_i32_e64 s[52:53], 34, v120
	v_cmp_gt_i32_e64 s[54:55], 34, v122
	s_nop 1
	s_and_b64 s[52:53], s[52:53], s[54:55]
	s_and_b64 s[52:53], s[52:53], s[60:61]
	s_nop 1
	v_cndmask_b32_e64 v221, v226, v134, s[52:53]
	v_cndmask_b32_e64 v134, v224, v134, s[52:53]
	v_max_f32_e32 v220, v220, v221
	v_cmp_le_i32_e64 s[52:53], 35, v120
	v_cmp_gt_i32_e64 s[54:55], 35, v122
	s_nop 1
	s_and_b64 s[52:53], s[52:53], s[54:55]
	s_and_b64 s[52:53], s[52:53], s[60:61]
	s_nop 1
	v_cndmask_b32_e64 v221, v226, v135, s[52:53]
	v_cndmask_b32_e64 v135, v224, v135, s[52:53]
	v_max_f32_e32 v220, v220, v221
	v_cmp_le_i32_e64 s[52:53], 48, v120
	v_cmp_gt_i32_e64 s[54:55], 48, v122
	s_nop 1
	s_and_b64 s[52:53], s[52:53], s[54:55]
	s_and_b64 s[52:53], s[52:53], s[60:61]
	s_nop 1
	v_cndmask_b32_e64 v221, v226, v136, s[52:53]
	v_cndmask_b32_e64 v136, v224, v136, s[52:53]
	v_max_f32_e32 v220, v220, v221
	v_cmp_le_i32_e64 s[52:53], 49, v120
	v_cmp_gt_i32_e64 s[54:55], 49, v122
	s_nop 1
	s_and_b64 s[52:53], s[52:53], s[54:55]
	s_and_b64 s[52:53], s[52:53], s[60:61]
	s_nop 1
	v_cndmask_b32_e64 v221, v226, v137, s[52:53]
	v_cndmask_b32_e64 v137, v224, v137, s[52:53]
	v_max_f32_e32 v220, v220, v221
	v_cmp_le_i32_e64 s[52:53], 50, v120
	v_cmp_gt_i32_e64 s[54:55], 50, v122
	s_nop 1
	s_and_b64 s[52:53], s[52:53], s[54:55]
	s_and_b64 s[52:53], s[52:53], s[60:61]
	s_nop 1
	v_cndmask_b32_e64 v221, v226, v138, s[52:53]
	v_cndmask_b32_e64 v138, v224, v138, s[52:53]
	v_max_f32_e32 v220, v220, v221
	v_cmp_le_i32_e64 s[52:53], 51, v120
	v_cmp_gt_i32_e64 s[54:55], 51, v122
	s_nop 1
	s_and_b64 s[52:53], s[52:53], s[54:55]
	s_and_b64 s[52:53], s[52:53], s[60:61]
	s_nop 1
	v_cndmask_b32_e64 v221, v226, v139, s[52:53]
	v_cndmask_b32_e64 v139, v224, v139, s[52:53]
	v_max_f32_e32 v220, v220, v221
	v_mov_b32_e32 v221, v220
	s_nop 1
	v_permlane16_swap_b32_e32 v220, v221
	v_max_f32_e32 v220, v220, v221
	v_mov_b32_e32 v221, v220
	s_nop 1
	v_permlane32_swap_b32_e32 v220, v221
	v_max_f32_e32 v220, v220, v221
	v_max_f32_e32 v222, v80, v220
	v_sub_f32_e32 v223, v80, v222
	v_exp_f32_e32 v228, v223
	v_mov_b32_e32 v80, v222
	v_sub_f32_e32 v124, v124, v222
	v_sub_f32_e32 v125, v125, v222
	v_sub_f32_e32 v126, v126, v222
	v_sub_f32_e32 v127, v127, v222
	v_sub_f32_e32 v128, v128, v222
	v_sub_f32_e32 v129, v129, v222
	v_sub_f32_e32 v130, v130, v222
	v_sub_f32_e32 v131, v131, v222
	v_sub_f32_e32 v132, v132, v222
	v_sub_f32_e32 v133, v133, v222
	v_sub_f32_e32 v134, v134, v222
	v_sub_f32_e32 v135, v135, v222
	v_sub_f32_e32 v136, v136, v222
	v_sub_f32_e32 v137, v137, v222
	v_sub_f32_e32 v138, v138, v222
	v_sub_f32_e32 v139, v139, v222
	v_exp_f32_e32 v124, v124
	v_exp_f32_e32 v125, v125
	v_exp_f32_e32 v126, v126
	v_exp_f32_e32 v127, v127
	v_exp_f32_e32 v128, v128
	v_exp_f32_e32 v129, v129
	v_exp_f32_e32 v130, v130
	v_exp_f32_e32 v131, v131
	v_exp_f32_e32 v132, v132
	v_exp_f32_e32 v133, v133
	v_exp_f32_e32 v134, v134
	v_exp_f32_e32 v135, v135
	v_exp_f32_e32 v136, v136
	v_exp_f32_e32 v137, v137
	v_exp_f32_e32 v138, v138
	v_exp_f32_e32 v139, v139
	v_mul_f32_e32 v82, v82, v228
	v_add_f32_e32 v232, 0, v124
	v_add_f32_e32 v232, v232, v125
	v_add_f32_e32 v232, v232, v126
	v_add_f32_e32 v232, v232, v127
	v_add_f32_e32 v232, v232, v128
	v_add_f32_e32 v232, v232, v129
	v_add_f32_e32 v232, v232, v130
	v_add_f32_e32 v232, v232, v131
	v_add_f32_e32 v232, v232, v132
	v_add_f32_e32 v232, v232, v133
	v_add_f32_e32 v232, v232, v134
	v_add_f32_e32 v232, v232, v135
	v_add_f32_e32 v232, v232, v136
	v_add_f32_e32 v232, v232, v137
	v_add_f32_e32 v232, v232, v138
	v_add_f32_e32 v232, v232, v139
	v_add_f32_e32 v82, v82, v232
	v_pk_mul_f32 v[48:49], v[48:49], v[228:229] op_sel_hi:[1,0]
	v_pk_mul_f32 v[50:51], v[50:51], v[228:229] op_sel_hi:[1,0]
	v_pk_mul_f32 v[52:53], v[52:53], v[228:229] op_sel_hi:[1,0]
	v_pk_mul_f32 v[54:55], v[54:55], v[228:229] op_sel_hi:[1,0]
	v_pk_mul_f32 v[56:57], v[56:57], v[228:229] op_sel_hi:[1,0]
	v_pk_mul_f32 v[58:59], v[58:59], v[228:229] op_sel_hi:[1,0]
	v_pk_mul_f32 v[60:61], v[60:61], v[228:229] op_sel_hi:[1,0]
	v_pk_mul_f32 v[62:63], v[62:63], v[228:229] op_sel_hi:[1,0]
	v_cvt_pk_bf16_f32 v204, v124, v125
	v_cvt_pk_bf16_f32 v205, v126, v127
	v_cvt_pk_bf16_f32 v206, v128, v129
	v_cvt_pk_bf16_f32 v207, v130, v131
	v_cvt_pk_bf16_f32 v208, v132, v133
	v_cvt_pk_bf16_f32 v209, v134, v135
	v_cvt_pk_bf16_f32 v210, v136, v137
	v_cvt_pk_bf16_f32 v211, v138, v139
	v_mov_b32_e32 v220, v226
	v_cmp_le_i32_e64 s[52:53], 0, v121
	v_cmp_gt_i32_e64 s[54:55], 0, v123
	s_nop 1
	s_and_b64 s[52:53], s[52:53], s[54:55]
	s_and_b64 s[52:53], s[52:53], s[62:63]
	s_nop 1
	v_cndmask_b32_e64 v221, v226, v140, s[52:53]
	v_cndmask_b32_e64 v140, v224, v140, s[52:53]
	v_max_f32_e32 v220, v220, v221
	v_cmp_le_i32_e64 s[52:53], 1, v121
	v_cmp_gt_i32_e64 s[54:55], 1, v123
	s_nop 1
	s_and_b64 s[52:53], s[52:53], s[54:55]
	s_and_b64 s[52:53], s[52:53], s[62:63]
	s_nop 1
	v_cndmask_b32_e64 v221, v226, v141, s[52:53]
	v_cndmask_b32_e64 v141, v224, v141, s[52:53]
	v_max_f32_e32 v220, v220, v221
	v_cmp_le_i32_e64 s[52:53], 2, v121
	v_cmp_gt_i32_e64 s[54:55], 2, v123
	s_nop 1
	s_and_b64 s[52:53], s[52:53], s[54:55]
	s_and_b64 s[52:53], s[52:53], s[62:63]
	s_nop 1
	v_cndmask_b32_e64 v221, v226, v142, s[52:53]
	v_cndmask_b32_e64 v142, v224, v142, s[52:53]
	v_max_f32_e32 v220, v220, v221
	v_cmp_le_i32_e64 s[52:53], 3, v121
	v_cmp_gt_i32_e64 s[54:55], 3, v123
	s_nop 1
	s_and_b64 s[52:53], s[52:53], s[54:55]
	s_and_b64 s[52:53], s[52:53], s[62:63]
	s_nop 1
	v_cndmask_b32_e64 v221, v226, v143, s[52:53]
	v_cndmask_b32_e64 v143, v224, v143, s[52:53]
	v_max_f32_e32 v220, v220, v221
	v_cmp_le_i32_e64 s[52:53], 16, v121
	v_cmp_gt_i32_e64 s[54:55], 16, v123
	s_nop 1
	s_and_b64 s[52:53], s[52:53], s[54:55]
	s_and_b64 s[52:53], s[52:53], s[62:63]
	s_nop 1
	v_cndmask_b32_e64 v221, v226, v144, s[52:53]
	v_cndmask_b32_e64 v144, v224, v144, s[52:53]
	v_max_f32_e32 v220, v220, v221
	v_cmp_le_i32_e64 s[52:53], 17, v121
	v_cmp_gt_i32_e64 s[54:55], 17, v123
	s_nop 1
	s_and_b64 s[52:53], s[52:53], s[54:55]
	s_and_b64 s[52:53], s[52:53], s[62:63]
	s_nop 1
	v_cndmask_b32_e64 v221, v226, v145, s[52:53]
	v_cndmask_b32_e64 v145, v224, v145, s[52:53]
	v_max_f32_e32 v220, v220, v221
	v_cmp_le_i32_e64 s[52:53], 18, v121
	v_cmp_gt_i32_e64 s[54:55], 18, v123
	s_nop 1
	s_and_b64 s[52:53], s[52:53], s[54:55]
	s_and_b64 s[52:53], s[52:53], s[62:63]
	s_nop 1
	v_cndmask_b32_e64 v221, v226, v146, s[52:53]
	v_cndmask_b32_e64 v146, v224, v146, s[52:53]
	v_max_f32_e32 v220, v220, v221
	v_cmp_le_i32_e64 s[52:53], 19, v121
	v_cmp_gt_i32_e64 s[54:55], 19, v123
	s_nop 1
	s_and_b64 s[52:53], s[52:53], s[54:55]
	s_and_b64 s[52:53], s[52:53], s[62:63]
	s_nop 1
	v_cndmask_b32_e64 v221, v226, v147, s[52:53]
	v_cndmask_b32_e64 v147, v224, v147, s[52:53]
	v_max_f32_e32 v220, v220, v221
	v_cmp_le_i32_e64 s[52:53], 32, v121
	v_cmp_gt_i32_e64 s[54:55], 32, v123
	s_nop 1
	s_and_b64 s[52:53], s[52:53], s[54:55]
	s_and_b64 s[52:53], s[52:53], s[62:63]
	s_nop 1
	v_cndmask_b32_e64 v221, v226, v148, s[52:53]
	v_cndmask_b32_e64 v148, v224, v148, s[52:53]
	v_max_f32_e32 v220, v220, v221
	v_cmp_le_i32_e64 s[52:53], 33, v121
	v_cmp_gt_i32_e64 s[54:55], 33, v123
	s_nop 1
	s_and_b64 s[52:53], s[52:53], s[54:55]
	s_and_b64 s[52:53], s[52:53], s[62:63]
	s_nop 1
	v_cndmask_b32_e64 v221, v226, v149, s[52:53]
	v_cndmask_b32_e64 v149, v224, v149, s[52:53]
	v_max_f32_e32 v220, v220, v221
	v_cmp_le_i32_e64 s[52:53], 34, v121
	v_cmp_gt_i32_e64 s[54:55], 34, v123
	s_nop 1
	s_and_b64 s[52:53], s[52:53], s[54:55]
	s_and_b64 s[52:53], s[52:53], s[62:63]
	s_nop 1
	v_cndmask_b32_e64 v221, v226, v150, s[52:53]
	v_cndmask_b32_e64 v150, v224, v150, s[52:53]
	v_max_f32_e32 v220, v220, v221
	v_cmp_le_i32_e64 s[52:53], 35, v121
	v_cmp_gt_i32_e64 s[54:55], 35, v123
	s_nop 1
	s_and_b64 s[52:53], s[52:53], s[54:55]
	s_and_b64 s[52:53], s[52:53], s[62:63]
	s_nop 1
	v_cndmask_b32_e64 v221, v226, v151, s[52:53]
	v_cndmask_b32_e64 v151, v224, v151, s[52:53]
	v_max_f32_e32 v220, v220, v221
	v_cmp_le_i32_e64 s[52:53], 48, v121
	v_cmp_gt_i32_e64 s[54:55], 48, v123
	s_nop 1
	s_and_b64 s[52:53], s[52:53], s[54:55]
	s_and_b64 s[52:53], s[52:53], s[62:63]
	s_nop 1
	v_cndmask_b32_e64 v221, v226, v154, s[52:53]
	v_cndmask_b32_e64 v154, v224, v154, s[52:53]
	v_max_f32_e32 v220, v220, v221
	v_cmp_le_i32_e64 s[52:53], 49, v121
	v_cmp_gt_i32_e64 s[54:55], 49, v123
	s_nop 1
	s_and_b64 s[52:53], s[52:53], s[54:55]
	s_and_b64 s[52:53], s[52:53], s[62:63]
	s_nop 1
	v_cndmask_b32_e64 v221, v226, v155, s[52:53]
	v_cndmask_b32_e64 v155, v224, v155, s[52:53]
	v_max_f32_e32 v220, v220, v221
	v_cmp_le_i32_e64 s[52:53], 50, v121
	v_cmp_gt_i32_e64 s[54:55], 50, v123
	s_nop 1
	s_and_b64 s[52:53], s[52:53], s[54:55]
	s_and_b64 s[52:53], s[52:53], s[62:63]
	s_nop 1
	v_cndmask_b32_e64 v221, v226, v156, s[52:53]
	v_cndmask_b32_e64 v156, v224, v156, s[52:53]
	v_max_f32_e32 v220, v220, v221
	v_cmp_le_i32_e64 s[52:53], 51, v121
	v_cmp_gt_i32_e64 s[54:55], 51, v123
	s_nop 1
	s_and_b64 s[52:53], s[52:53], s[54:55]
	s_and_b64 s[52:53], s[52:53], s[62:63]
	s_nop 1
	v_cndmask_b32_e64 v221, v226, v157, s[52:53]
	v_cndmask_b32_e64 v157, v224, v157, s[52:53]
	v_max_f32_e32 v220, v220, v221
	v_mov_b32_e32 v221, v220
	s_nop 1
	v_permlane16_swap_b32_e32 v220, v221
	v_max_f32_e32 v220, v220, v221
	v_mov_b32_e32 v221, v220
	s_nop 1
	v_permlane32_swap_b32_e32 v220, v221
	v_max_f32_e32 v220, v220, v221
	v_max_f32_e32 v222, v81, v220
	v_sub_f32_e32 v223, v81, v222
	v_exp_f32_e32 v230, v223
	v_mov_b32_e32 v81, v222
	v_sub_f32_e32 v140, v140, v222
	v_sub_f32_e32 v141, v141, v222
	v_sub_f32_e32 v142, v142, v222
	v_sub_f32_e32 v143, v143, v222
	v_sub_f32_e32 v144, v144, v222
	v_sub_f32_e32 v145, v145, v222
	v_sub_f32_e32 v146, v146, v222
	v_sub_f32_e32 v147, v147, v222
	v_sub_f32_e32 v148, v148, v222
	v_sub_f32_e32 v149, v149, v222
	v_sub_f32_e32 v150, v150, v222
	v_sub_f32_e32 v151, v151, v222
	v_sub_f32_e32 v154, v154, v222
	v_sub_f32_e32 v155, v155, v222
	v_sub_f32_e32 v156, v156, v222
	v_sub_f32_e32 v157, v157, v222
	v_exp_f32_e32 v140, v140
	v_exp_f32_e32 v141, v141
	v_exp_f32_e32 v142, v142
	v_exp_f32_e32 v143, v143
	v_exp_f32_e32 v144, v144
	v_exp_f32_e32 v145, v145
	v_exp_f32_e32 v146, v146
	v_exp_f32_e32 v147, v147
	v_exp_f32_e32 v148, v148
	v_exp_f32_e32 v149, v149
	v_exp_f32_e32 v150, v150
	v_exp_f32_e32 v151, v151
	v_exp_f32_e32 v154, v154
	v_exp_f32_e32 v155, v155
	v_exp_f32_e32 v156, v156
	v_exp_f32_e32 v157, v157
	v_mul_f32_e32 v83, v83, v230
	v_add_f32_e32 v232, 0, v140
	v_add_f32_e32 v232, v232, v141
	v_add_f32_e32 v232, v232, v142
	v_add_f32_e32 v232, v232, v143
	v_add_f32_e32 v232, v232, v144
	v_add_f32_e32 v232, v232, v145
	v_add_f32_e32 v232, v232, v146
	v_add_f32_e32 v232, v232, v147
	v_add_f32_e32 v232, v232, v148
	v_add_f32_e32 v232, v232, v149
	v_add_f32_e32 v232, v232, v150
	v_add_f32_e32 v232, v232, v151
	v_add_f32_e32 v232, v232, v154
	v_add_f32_e32 v232, v232, v155
	v_add_f32_e32 v232, v232, v156
	v_add_f32_e32 v232, v232, v157
	v_add_f32_e32 v83, v83, v232
	v_pk_mul_f32 v[64:65], v[64:65], v[230:231] op_sel_hi:[1,0]
	v_pk_mul_f32 v[66:67], v[66:67], v[230:231] op_sel_hi:[1,0]
	v_pk_mul_f32 v[68:69], v[68:69], v[230:231] op_sel_hi:[1,0]
	v_pk_mul_f32 v[70:71], v[70:71], v[230:231] op_sel_hi:[1,0]
	v_pk_mul_f32 v[72:73], v[72:73], v[230:231] op_sel_hi:[1,0]
	v_pk_mul_f32 v[74:75], v[74:75], v[230:231] op_sel_hi:[1,0]
	v_pk_mul_f32 v[76:77], v[76:77], v[230:231] op_sel_hi:[1,0]
	v_pk_mul_f32 v[78:79], v[78:79], v[230:231] op_sel_hi:[1,0]
	v_cvt_pk_bf16_f32 v212, v140, v141
	v_cvt_pk_bf16_f32 v213, v142, v143
	v_cvt_pk_bf16_f32 v214, v144, v145
	v_cvt_pk_bf16_f32 v215, v146, v147
	v_cvt_pk_bf16_f32 v216, v148, v149
	v_cvt_pk_bf16_f32 v217, v150, v151
	v_cvt_pk_bf16_f32 v218, v154, v155
	v_cvt_pk_bf16_f32 v219, v156, v157
	s_waitcnt lgkmcnt(0)
	v_mfma_f32_16x16x32_bf16 v[48:51], v[160:163], v[204:207], v[48:51]
	v_mfma_f32_16x16x32_bf16 v[64:67], v[160:163], v[212:215], v[64:67]
	v_mfma_f32_16x16x32_bf16 v[48:51], v[164:167], v[208:211], v[48:51]
	v_mfma_f32_16x16x32_bf16 v[64:67], v[164:167], v[216:219], v[64:67]
	v_mfma_f32_16x16x32_bf16 v[52:55], v[168:171], v[204:207], v[52:55]
	v_mfma_f32_16x16x32_bf16 v[68:71], v[168:171], v[212:215], v[68:71]
	v_mfma_f32_16x16x32_bf16 v[52:55], v[172:175], v[208:211], v[52:55]
	v_mfma_f32_16x16x32_bf16 v[68:71], v[172:175], v[216:219], v[68:71]
	v_mfma_f32_16x16x32_bf16 v[56:59], v[176:179], v[204:207], v[56:59]
	v_mfma_f32_16x16x32_bf16 v[72:75], v[176:179], v[212:215], v[72:75]
	v_mfma_f32_16x16x32_bf16 v[56:59], v[180:183], v[208:211], v[56:59]
	v_mfma_f32_16x16x32_bf16 v[72:75], v[180:183], v[216:219], v[72:75]
	v_mfma_f32_16x16x32_bf16 v[60:63], v[184:187], v[204:207], v[60:63]
	v_mfma_f32_16x16x32_bf16 v[76:79], v[184:187], v[212:215], v[76:79]
	v_mfma_f32_16x16x32_bf16 v[60:63], v[188:191], v[208:211], v[60:63]
	v_mfma_f32_16x16x32_bf16 v[76:79], v[188:191], v[216:219], v[76:79]
.Lnsa_fin_17:
	s_cmp_lt_i32 s41, 0
	s_cbranch_scc1 .Lnsa_brk_9
	s_or_b32 s65, s42, s40
	s_cmp_lt_i32 s65, 0
	s_cbranch_scc0 .Lnsa_w4_19
	s_waitcnt vmcnt(0)
	s_branch .Lnsa_wd_20

.Lnsa_wd_20:
	s_and_b32 s65, s27, 1
	s_mul_i32 s50, s65, 0x4800
	s_add_i32 s27, s27, 1
	v_add_u32_e32 v225, s50, v114
	ds_write_b128 v225, v[96:99]
	ds_write_b128 v225, v[100:103] offset:9216
	s_waitcnt lgkmcnt(0)
	s_barrier
	s_mov_b32 s43, s41
	s_ff1_i32_b32 s41, s38
	s_add_i32 s65, s38, -1
	s_and_b32 s38, s38, s65
	s_cmp_lt_i32 s41, 0
	s_cbranch_scc1 .Lnsa_noload_21
	s_mul_i32 s65, s41, 0x18000
	s_add_u32 s56, s46, s65
	s_addc_u32 s57, s47, 0
	s_lshl_b32 s65, s41, 7
	s_add_u32 s58, s48, s65
	s_addc_u32 s59, s49, 0
	global_load_dwordx4 v[96:99], v117, s[56:57]
	global_load_dwordx4 v[100:103], v118, s[58:59]

.Lnsa_fin_26:
	s_cmp_lt_i32 s42, 0
	s_cbranch_scc1 .Lnsa_brk_9
	s_or_b32 s65, s40, s41
	s_cmp_lt_i32 s65, 0
	s_cbranch_scc0 .Lnsa_w4_28
	s_waitcnt vmcnt(0)
	s_branch .Lnsa_wd_29

.Lnsa_wd_29:
	s_and_b32 s65, s27, 1
	s_mul_i32 s50, s65, 0x4800
	s_add_i32 s27, s27, 1
	v_add_u32_e32 v225, s50, v114
	ds_write_b128 v225, v[104:107]
	ds_write_b128 v225, v[108:111] offset:9216
	s_waitcnt lgkmcnt(0)
	s_barrier
	s_mov_b32 s43, s42
	s_ff1_i32_b32 s42, s38
	s_add_i32 s65, s38, -1
	s_and_b32 s38, s38, s65
	s_cmp_lt_i32 s42, 0
	s_cbranch_scc1 .Lnsa_noload_30
	s_mul_i32 s65, s42, 0x18000
	s_add_u32 s56, s46, s65
	s_addc_u32 s57, s47, 0
	s_lshl_b32 s65, s42, 7
	s_add_u32 s58, s48, s65
	s_addc_u32 s59, s49, 0
	global_load_dwordx4 v[104:107], v117, s[56:57]
	global_load_dwordx4 v[108:111], v118, s[58:59]

.Lnsa_fin_35:
	s_branch .Lnsa_loop_8
.Lnsa_brk_9:
	s_nop 7
	s_lshl_b32 s3, s30, 11
	v_mov_b32_e32 v221, v82
	s_nop 1
	v_permlane16_swap_b32_e32 v82, v221
	v_add_f32_e32 v82, v82, v221
	v_mov_b32_e32 v221, v82
	s_nop 1
	v_permlane32_swap_b32_e32 v82, v221
	v_add_f32_e32 v82, v82, v221
	v_max_f32_e32 v220, 0xda24260, v82
	s_cmp_eq_u32 s37, 1
	s_cselect_b64 vcc, -1, 0
	s_nop 1
	v_cndmask_b32_e32 v222, v119, v158, vcc
	v_lshlrev_b32_e32 v222, 16, v222
	v_div_scale_f32 v240, s[52:53], v220, v220, v222
	v_rcp_f32_e32 v241, v240
	v_div_scale_f32 v242, vcc, v222, v220, v222
	v_fma_f32 v243, -v240, v241, 1.0
	v_fmac_f32_e32 v241, v243, v241
	v_mul_f32_e32 v243, v242, v241
	v_fma_f32 v244, -v240, v243, v242
	v_fmac_f32_e32 v243, v244, v241
	v_fma_f32 v240, -v240, v243, v242
	s_nop 1
	v_div_fmas_f32 v240, v240, v241, v243
	v_div_fixup_f32 v228, v240, v220, v222
	v_pk_fma_f32 v[16:17], v[48:49], v[228:229], v[16:17] op_sel_hi:[1,0,1]
	v_pk_fma_f32 v[18:19], v[50:51], v[228:229], v[18:19] op_sel_hi:[1,0,1]
	v_pk_fma_f32 v[20:21], v[52:53], v[228:229], v[20:21] op_sel_hi:[1,0,1]
	v_pk_fma_f32 v[22:23], v[54:55], v[228:229], v[22:23] op_sel_hi:[1,0,1]
	v_pk_fma_f32 v[24:25], v[56:57], v[228:229], v[24:25] op_sel_hi:[1,0,1]
	v_pk_fma_f32 v[26:27], v[58:59], v[228:229], v[26:27] op_sel_hi:[1,0,1]
	v_pk_fma_f32 v[28:29], v[60:61], v[228:229], v[28:29] op_sel_hi:[1,0,1]
	v_pk_fma_f32 v[30:31], v[62:63], v[228:229], v[30:31] op_sel_hi:[1,0,1]
	v_mov_b32_e32 v221, v83
	s_nop 1
	v_permlane16_swap_b32_e32 v83, v221
	v_add_f32_e32 v83, v83, v221
	v_mov_b32_e32 v221, v83
	s_nop 1
	v_permlane32_swap_b32_e32 v83, v221
	v_add_f32_e32 v83, v83, v221
	v_max_f32_e32 v220, 0xda24260, v83
	s_cmp_eq_u32 s37, 1
	s_cselect_b64 vcc, -1, 0
	s_nop 1
	v_cndmask_b32_e32 v222, v159, v233, vcc
	v_lshlrev_b32_e32 v222, 16, v222
	v_div_scale_f32 v240, s[52:53], v220, v220, v222
	v_rcp_f32_e32 v241, v240
	v_div_scale_f32 v242, vcc, v222, v220, v222
	v_fma_f32 v243, -v240, v241, 1.0
	v_fmac_f32_e32 v241, v243, v241
	v_mul_f32_e32 v243, v242, v241
	v_fma_f32 v244, -v240, v243, v242
	v_fmac_f32_e32 v243, v244, v241
	v_fma_f32 v240, -v240, v243, v242
	s_nop 1
	v_div_fmas_f32 v240, v240, v241, v243
	v_div_fixup_f32 v228, v240, v220, v222
	v_pk_fma_f32 v[32:33], v[64:65], v[228:229], v[32:33] op_sel_hi:[1,0,1]
	v_pk_fma_f32 v[34:35], v[66:67], v[228:229], v[34:35] op_sel_hi:[1,0,1]
	v_pk_fma_f32 v[36:37], v[68:69], v[228:229], v[36:37] op_sel_hi:[1,0,1]
	v_pk_fma_f32 v[38:39], v[70:71], v[228:229], v[38:39] op_sel_hi:[1,0,1]
	v_pk_fma_f32 v[40:41], v[72:73], v[228:229], v[40:41] op_sel_hi:[1,0,1]
	v_pk_fma_f32 v[42:43], v[74:75], v[228:229], v[42:43] op_sel_hi:[1,0,1]
	v_pk_fma_f32 v[44:45], v[76:77], v[228:229], v[44:45] op_sel_hi:[1,0,1]
	v_pk_fma_f32 v[46:47], v[78:79], v[228:229], v[46:47] op_sel_hi:[1,0,1]
	s_add_i32 s37, s37, 1
	s_cmp_lt_u32 s37, 2
	s_cbranch_scc1 .Lnsa_br
	s_lshl_b32 s3, s30, 11
	s_add_u32 s8, s96, 0x9000000
	s_addc_u32 s9, s97, 0
	v_add_u32_e32 v223, s3, v86
	v_lshlrev_b32_e32 v223, 10, v223
	s_lshl_b32 s2, s36, 7
	v_add_u32_e32 v223, s2, v223
	v_lshl_add_u32 v223, v113, 3, v223
	v_cvt_pk_bf16_f32 v240, v16, v17
	v_cvt_pk_bf16_f32 v241, v18, v19
	global_store_dwordx2 v223, v[240:241], s[8:9] offset:0
	v_cvt_pk_bf16_f32 v240, v20, v21
	v_cvt_pk_bf16_f32 v241, v22, v23
	global_store_dwordx2 v223, v[240:241], s[8:9] offset:32
	v_cvt_pk_bf16_f32 v240, v24, v25
	v_cvt_pk_bf16_f32 v241, v26, v27
	global_store_dwordx2 v223, v[240:241], s[8:9] offset:64
	v_cvt_pk_bf16_f32 v240, v28, v29
	v_cvt_pk_bf16_f32 v241, v30, v31
	global_store_dwordx2 v223, v[240:241], s[8:9] offset:96
	v_add_u32_e32 v223, s3, v87
	v_lshlrev_b32_e32 v223, 10, v223
	s_lshl_b32 s2, s36, 7
	v_add_u32_e32 v223, s2, v223
	v_lshl_add_u32 v223, v113, 3, v223
	v_cvt_pk_bf16_f32 v240, v32, v33
	v_cvt_pk_bf16_f32 v241, v34, v35
	global_store_dwordx2 v223, v[240:241], s[8:9] offset:0
	v_cvt_pk_bf16_f32 v240, v36, v37
	v_cvt_pk_bf16_f32 v241, v38, v39
	global_store_dwordx2 v223, v[240:241], s[8:9] offset:32
	v_cvt_pk_bf16_f32 v240, v40, v41
	v_cvt_pk_bf16_f32 v241, v42, v43
	global_store_dwordx2 v223, v[240:241], s[8:9] offset:64
	v_cvt_pk_bf16_f32 v240, v44, v45
	v_cvt_pk_bf16_f32 v241, v46, v47
	global_store_dwordx2 v223, v[240:241], s[8:9] offset:96
	s_add_i32 s26, s26, s92
	s_cmpk_lt_i32 s26, 0x400
	s_cbranch_scc1 .Lnsa_task
.Lnsa_done:
	s_waitcnt vmcnt(0)
.LBB0_2167:
	v_readlane_b32 s0, v251, 24
	s_cmpk_gt_i32 s88, 0x7fff
	v_readlane_b32 s8, v251, 32
	v_readlane_b32 s9, v251, 33
	v_readlane_b32 s10, v251, 34
	v_readlane_b32 s11, v251, 35
	v_readlane_b32 s12, v251, 36
	v_readlane_b32 s13, v251, 37
	v_readlane_b32 s1, v251, 25
	v_readlane_b32 s2, v251, 26
	v_readlane_b32 s3, v251, 27
	v_readlane_b32 s4, v251, 28
	v_readlane_b32 s5, v251, 29
	v_readlane_b32 s6, v251, 30
	v_readlane_b32 s7, v251, 31
	v_readlane_b32 s14, v251, 38
	v_readlane_b32 s15, v251, 39
	s_cbranch_scc1 .LBB0_2170
	v_lshlrev_b32_e32 v0, 5, v152
	v_mov_b32_e32 v1, 0
	v_lshl_add_u64 v[2:3], s[8:9], 0, v[0:1]
	v_lshl_add_u64 v[4:5], s[10:11], 0, v[0:1]
	v_lshl_add_u64 v[6:7], s[12:13], 0, v[0:1]
	v_mbcnt_hi_u32_b32 v0, -1, v155
	v_and_b32_e32 v9, 64, v0
	s_ashr_i32 s89, s88, 31
	v_xor_b32_e32 v8, 1, v0
	v_add_u32_e32 v10, 64, v9
	s_lshl_b64 s[4:5], s[88:89], 10
	v_cmp_lt_i32_e32 vcc, v8, v10
	v_xor_b32_e32 v9, 2, v0
	s_add_u32 s0, s96, s4
	v_cndmask_b32_e32 v8, v0, v8, vcc
	v_cmp_lt_i32_e32 vcc, v9, v10
	v_xor_b32_e32 v11, 4, v0
	s_addc_u32 s1, s97, s5
	s_ashr_i32 s95, s94, 31
	v_cndmask_b32_e32 v9, v0, v9, vcc
	v_cmp_lt_i32_e32 vcc, v11, v10
	s_lshl_b64 s[2:3], s[94:95], 10
	s_add_u32 s4, s74, s4
	v_cndmask_b32_e32 v0, v0, v11, vcc
	v_lshlrev_b32_e32 v8, 2, v8
	v_lshlrev_b32_e32 v9, 2, v9
	v_lshlrev_b32_e32 v10, 2, v0
	v_lshlrev_b32_e32 v0, 4, v152
	s_addc_u32 s5, s75, s5
	s_brev_b32 s6, 32
	s_mov_b32 s7, 0x6000000
	s_mov_b32 s8, 0x1dd00000
	v_mov_b32_e32 v11, 0x3a27c5ac
	s_mov_b32 s9, 0x800000
	s_mov_b32 s10, s88
	global_load_dwordx4 v[56:59], v[2:3], off
	global_load_dwordx4 v[60:63], v[2:3], off offset:16
	global_load_dwordx4 v[64:67], v[4:5], off
	global_load_dwordx4 v[68:71], v[4:5], off offset:16
	global_load_dwordx4 v[72:75], v[6:7], off
	global_load_dwordx4 v[76:79], v[6:7], off offset:16
	s_add_u32 s76, s4, s6
	s_addc_u32 s77, s5, 0
	s_add_u32 s78, s4, s7
	s_addc_u32 s79, s5, 0
	s_add_u32 s80, s0, 0x7000000
	s_addc_u32 s81, s1, 0
	s_add_u32 s82, s0, s8
	s_addc_u32 s83, s1, 0
	s_mov_b32 s32, s10
	global_load_dwordx4 v[80:83], v0, s[4:5]
	global_load_dwordx4 v[84:87], v0, s[80:81]
	global_load_dwordx4 v[88:91], v0, s[76:77]
	global_load_dwordx4 v[92:95], v0, s[78:79]
	global_load_dwordx4 v[96:99], v0, s[82:83]
	v_lshl_add_u64 v[100:101], s[80:81], 0, v[0:1]
	s_add_i32 s32, s32, s94
	s_cmp_lt_i32 s32, 0x8000
	s_cselect_b32 s85, s2, 0
	s_cselect_b32 s91, s3, 0
	s_add_u32 s4, s4, s85
	s_addc_u32 s5, s5, s91
	s_add_u32 s76, s76, s85
	s_addc_u32 s77, s77, s91
	s_add_u32 s78, s78, s85
	s_addc_u32 s79, s79, s91
	s_add_u32 s80, s80, s85
	s_addc_u32 s81, s81, s91
	s_add_u32 s82, s82, s85
	s_addc_u32 s83, s83, s91
	global_load_dwordx4 v[104:107], v0, s[4:5]
	global_load_dwordx4 v[108:111], v0, s[80:81]
	global_load_dwordx4 v[112:115], v0, s[76:77]
	global_load_dwordx4 v[116:119], v0, s[78:79]
	global_load_dwordx4 v[120:123], v0, s[82:83]
	v_lshl_add_u64 v[124:125], s[80:81], 0, v[0:1]
	s_add_i32 s32, s32, s94
	s_cmp_lt_i32 s32, 0x8000
	s_cselect_b32 s85, s2, 0
	s_cselect_b32 s91, s3, 0
	s_add_u32 s4, s4, s85
	s_addc_u32 s5, s5, s91
	s_add_u32 s76, s76, s85
	s_addc_u32 s77, s77, s91
	s_add_u32 s78, s78, s85
	s_addc_u32 s79, s79, s91
	s_add_u32 s80, s80, s85
	s_addc_u32 s81, s81, s91
	s_add_u32 s82, s82, s85
	s_addc_u32 s83, s83, s91
	global_load_dwordx4 v[128:131], v0, s[4:5]
	global_load_dwordx4 v[132:135], v0, s[80:81]
	global_load_dwordx4 v[136:139], v0, s[76:77]
	global_load_dwordx4 v[140:143], v0, s[78:79]
	global_load_dwordx4 v[144:147], v0, s[82:83]
	v_lshl_add_u64 v[148:149], s[80:81], 0, v[0:1]
	s_add_i32 s32, s32, s94
	s_cmp_lt_i32 s32, 0x8000
	s_cselect_b32 s85, s2, 0
	s_cselect_b32 s91, s3, 0
	s_add_u32 s4, s4, s85
	s_addc_u32 s5, s5, s91
	s_add_u32 s76, s76, s85
	s_addc_u32 s77, s77, s91
	s_add_u32 s78, s78, s85
	s_addc_u32 s79, s79, s91
	s_add_u32 s80, s80, s85
	s_addc_u32 s81, s81, s91
	s_add_u32 s82, s82, s85
	s_addc_u32 s83, s83, s91
	s_waitcnt vmcnt(10)
	v_lshlrev_b32_e32 v160, 16, v84
	v_and_b32_e32 v161, 0xffff0000, v84
	v_lshlrev_b32_e32 v162, 16, v85
	v_and_b32_e32 v163, 0xffff0000, v85
	v_lshlrev_b32_e32 v164, 16, v86
	v_and_b32_e32 v165, 0xffff0000, v86
	v_lshlrev_b32_e32 v166, 16, v87
	v_and_b32_e32 v167, 0xffff0000, v87
	v_lshlrev_b32_e32 v168, 16, v80
	v_and_b32_e32 v169, 0xffff0000, v80
	v_lshlrev_b32_e32 v170, 16, v81
	v_and_b32_e32 v171, 0xffff0000, v81
	v_lshlrev_b32_e32 v172, 16, v82
	v_and_b32_e32 v173, 0xffff0000, v82
	v_lshlrev_b32_e32 v174, 16, v83
	v_and_b32_e32 v175, 0xffff0000, v83
	v_lshlrev_b32_e32 v176, 16, v88
	v_and_b32_e32 v177, 0xffff0000, v88
	v_lshlrev_b32_e32 v178, 16, v89
	v_and_b32_e32 v179, 0xffff0000, v89
	v_lshlrev_b32_e32 v180, 16, v90
	v_and_b32_e32 v181, 0xffff0000, v90
	v_lshlrev_b32_e32 v182, 16, v91
	v_and_b32_e32 v183, 0xffff0000, v91
	v_add_f32_e32 v192, 0, v160
	v_pk_mul_f32 v[184:185], v[168:169], v[176:177]
	v_pk_mul_f32 v[186:187], v[170:171], v[178:179]
	v_pk_mul_f32 v[188:189], v[172:173], v[180:181]
	v_pk_mul_f32 v[190:191], v[174:175], v[182:183]
	v_add_f32_e32 v192, v192, v161
	v_pk_mul_f32 v[184:185], v[184:185], v[56:57]
	v_add_f32_e32 v192, v192, v162
	v_pk_mul_f32 v[186:187], v[186:187], v[58:59]
	v_add_f32_e32 v192, v192, v163
	v_pk_mul_f32 v[188:189], v[188:189], v[60:61]
	v_add_f32_e32 v192, v192, v164
	v_pk_mul_f32 v[190:191], v[190:191], v[62:63]
	v_add_f32_e32 v192, v192, v165
	v_add_f32_e32 v192, v192, v166
	v_add_f32_e32 v192, v192, v167
	v_add_f32_e32 v196, 0, v184
	v_add_f32_e32 v196, v185, v196
	v_add_f32_e32 v196, v186, v196
	v_add_f32_e32 v196, v187, v196
	v_add_f32_e32 v196, v188, v196
	v_add_f32_e32 v196, v189, v196
	v_add_f32_e32 v196, v190, v196
	v_add_f32_e32 v196, v191, v196
	v_lshlrev_b32_e32 v168, 16, v92
	v_and_b32_e32 v169, 0xffff0000, v92
	v_add_f32_dpp v192, v192, v192 quad_perm:[1,0,3,2] row_mask:0xf bank_mask:0xf bound_ctrl:1
	v_add_f32_dpp v196, v196, v196 quad_perm:[1,0,3,2] row_mask:0xf bank_mask:0xf bound_ctrl:1
	v_lshlrev_b32_e32 v170, 16, v93
	v_and_b32_e32 v171, 0xffff0000, v93
	v_add_f32_dpp v192, v192, v192 quad_perm:[2,3,0,1] row_mask:0xf bank_mask:0xf bound_ctrl:1
	v_add_f32_dpp v196, v196, v196 quad_perm:[2,3,0,1] row_mask:0xf bank_mask:0xf bound_ctrl:1
	v_lshlrev_b32_e32 v172, 16, v94
	v_and_b32_e32 v173, 0xffff0000, v94
	v_add_f32_dpp v192, v192, v192 row_half_mirror row_mask:0xf bank_mask:0xf bound_ctrl:1
	v_add_f32_dpp v196, v196, v196 row_half_mirror row_mask:0xf bank_mask:0xf bound_ctrl:1
	v_lshlrev_b32_e32 v174, 16, v95
	v_and_b32_e32 v175, 0xffff0000, v95
	v_mul_f32_e32 v194, 0x3c800000, v192
	v_pk_add_f32 v[204:205], v[160:161], v[194:195] op_sel_hi:[1,0] neg_lo:[0,1] neg_hi:[0,1]
	v_pk_add_f32 v[206:207], v[162:163], v[194:195] op_sel_hi:[1,0] neg_lo:[0,1] neg_hi:[0,1]
	v_pk_add_f32 v[208:209], v[164:165], v[194:195] op_sel_hi:[1,0] neg_lo:[0,1] neg_hi:[0,1]
	v_pk_add_f32 v[210:211], v[166:167], v[194:195] op_sel_hi:[1,0] neg_lo:[0,1] neg_hi:[0,1]
	v_pk_mul_f32 v[184:185], v[204:205], v[204:205]
	v_pk_mul_f32 v[186:187], v[206:207], v[206:207]
	v_pk_mul_f32 v[188:189], v[208:209], v[208:209]
	v_pk_mul_f32 v[190:191], v[210:211], v[210:211]
	v_add_f32_e32 v198, v184, v185
	v_add_f32_e32 v198, v186, v198
	v_add_f32_e32 v198, v187, v198
	v_add_f32_e32 v198, v188, v198
	v_add_f32_e32 v198, v189, v198
	v_add_f32_e32 v198, v190, v198
	v_add_f32_e32 v198, v191, v198
	v_lshlrev_b32_e32 v176, 16, v96
	v_and_b32_e32 v177, 0xffff0000, v96
	v_add_f32_dpp v198, v198, v198 quad_perm:[1,0,3,2] row_mask:0xf bank_mask:0xf bound_ctrl:1
	v_lshlrev_b32_e32 v178, 16, v97
	v_and_b32_e32 v179, 0xffff0000, v97
	v_add_f32_dpp v198, v198, v198 quad_perm:[2,3,0,1] row_mask:0xf bank_mask:0xf bound_ctrl:1
	v_lshlrev_b32_e32 v180, 16, v98
	v_and_b32_e32 v181, 0xffff0000, v98
	v_add_f32_dpp v198, v198, v198 row_half_mirror row_mask:0xf bank_mask:0xf bound_ctrl:1
	v_lshlrev_b32_e32 v182, 16, v99
	v_and_b32_e32 v183, 0xffff0000, v99
	v_fmamk_f32 v198, v198, 0x3c800000, v11
	v_mul_f32_e32 v199, 0x4b800000, v198
	v_cmp_gt_f32_e32 vcc, s9, v198
	s_nop 1
	v_cndmask_b32_e32 v198, v198, v199, vcc
	v_rsq_f32_e32 v198, v198
	s_nop 0
	v_mul_f32_e32 v200, 0x45800000, v198
	v_cndmask_b32_e32 v200, v198, v200, vcc
	v_pk_mul_f32 v[204:205], v[204:205], v[200:201] op_sel_hi:[1,0]
	v_pk_mul_f32 v[206:207], v[206:207], v[200:201] op_sel_hi:[1,0]
	v_pk_mul_f32 v[208:209], v[208:209], v[200:201] op_sel_hi:[1,0]
	v_pk_mul_f32 v[210:211], v[210:211], v[200:201] op_sel_hi:[1,0]
	v_pk_fma_f32 v[204:205], v[64:65], v[204:205], v[72:73]
	v_pk_fma_f32 v[206:207], v[66:67], v[206:207], v[74:75]
	v_pk_fma_f32 v[208:209], v[68:69], v[208:209], v[76:77]
	v_pk_fma_f32 v[210:211], v[70:71], v[210:211], v[78:79]
	v_pk_fma_f32 v[204:205], v[196:197], v[168:169], v[204:205] op_sel_hi:[0,1,1]
	v_pk_fma_f32 v[206:207], v[196:197], v[170:171], v[206:207] op_sel_hi:[0,1,1]
	v_pk_fma_f32 v[208:209], v[196:197], v[172:173], v[208:209] op_sel_hi:[0,1,1]
	v_pk_fma_f32 v[210:211], v[196:197], v[174:175], v[210:211] op_sel_hi:[0,1,1]
	v_pk_mul_f32 v[204:205], v[204:205], v[176:177]
	v_pk_mul_f32 v[206:207], v[206:207], v[178:179]
	v_pk_mul_f32 v[208:209], v[208:209], v[180:181]
	v_pk_mul_f32 v[210:211], v[210:211], v[182:183]
	v_cvt_pk_bf16_f32 v212, v204, v205
	v_cvt_pk_bf16_f32 v213, v206, v207
	v_cvt_pk_bf16_f32 v214, v208, v209
	v_cvt_pk_bf16_f32 v215, v210, v211
	global_store_dwordx4 v[100:101], v[212:215], off
	s_add_i32 s10, s10, s94
	s_cmp_lt_i32 s10, 0x8000
	s_cbranch_scc0 .Lrwp_done
